# P6 GEMM epilogue: residual pieces and row scales requested up front, waits count only those loads
# baseline (speedup 1.0000x reference)
.LBB0_1227:
	v_lshl_add_u32 v148, s34, 8, v1
	v_lshl_or_b32 v146, s12, 8, v153
	v_ashrrev_i32_e32 v149, 31, v148
	v_ashrrev_i32_e32 v147, 31, v146
	v_lshlrev_b64 v[150:151], 10, v[148:149]
	v_lshl_add_u64 v[150:151], v[150:151], 0, v[146:147]
	v_lshlrev_b64 v[162:163], 1, v[150:151]
	v_lshl_add_u64 v[150:151], s[96:97], 0, v[162:163]
	v_lshl_add_u64 v[130:131], v[148:149], 2, s[10:11]
	v_mov_b32_e32 v133, 0
	v_mov_b32_e32 v137, 0
	global_load_dwordx4 v[180:183], v[150:151], off
	global_load_dword v244, v[130:131], off
	global_load_dwordx4 v[184:187], v[150:151], off offset:256
	v_mov_b32_e32 v136, 0x8000
	v_lshl_add_u64 v[138:139], v[150:151], 0, v[136:137]
	global_load_dwordx4 v[188:191], v[138:139], off
	global_load_dword v245, v[130:131], off offset:64
	global_load_dwordx4 v[192:195], v[138:139], off offset:256
	v_mov_b32_e32 v132, 0x10000
	v_lshl_add_u64 v[134:135], v[150:151], 0, v[132:133]
	global_load_dwordx4 v[196:199], v[134:135], off
	global_load_dword v246, v[130:131], off offset:128
	global_load_dwordx4 v[200:203], v[134:135], off offset:256
	v_mov_b32_e32 v136, 0x18000
	v_lshl_add_u64 v[138:139], v[150:151], 0, v[136:137]
	global_load_dwordx4 v[204:207], v[138:139], off
	global_load_dword v247, v[130:131], off offset:192
	global_load_dwordx4 v[208:211], v[138:139], off offset:256
	v_mov_b32_e32 v132, 0x40000
	v_lshl_add_u64 v[134:135], v[150:151], 0, v[132:133]
	global_load_dwordx4 v[212:215], v[134:135], off
	global_load_dword v248, v[130:131], off offset:512
	global_load_dwordx4 v[216:219], v[134:135], off offset:256
	v_mov_b32_e32 v136, 0x48000
	v_lshl_add_u64 v[138:139], v[150:151], 0, v[136:137]
	global_load_dwordx4 v[220:223], v[138:139], off
	global_load_dword v249, v[130:131], off offset:576
	global_load_dwordx4 v[224:227], v[138:139], off offset:256
	v_mov_b32_e32 v132, 0x50000
	v_lshl_add_u64 v[134:135], v[150:151], 0, v[132:133]
	global_load_dwordx4 v[228:231], v[134:135], off
	global_load_dword v250, v[130:131], off offset:640
	global_load_dwordx4 v[232:235], v[134:135], off offset:256
	v_mov_b32_e32 v136, 0x58000
	v_lshl_add_u64 v[138:139], v[150:151], 0, v[136:137]
	global_load_dwordx4 v[236:239], v[138:139], off
	global_load_dword v251, v[130:131], off offset:704
	global_load_dwordx4 v[240:243], v[138:139], off offset:256
	s_waitcnt vmcnt(22)
	v_mov_b32_e32 v158, v180
	v_mov_b32_e32 v159, v181
	v_mov_b32_e32 v160, v182
	v_mov_b32_e32 v161, v183
	v_lshl_add_u64 v[150:151], v[148:149], 2, s[10:11]
	v_mov_b32_e32 v164, v244
	v_lshl_add_u64 v[166:167], s[6:7], 0, v[162:163]
	v_or_b32_e32 v162, 0x100, v162
	v_lshl_add_u64 v[168:169], s[96:97], 0, v[162:163]
	s_lshl_b32 s34, s12, 2
	s_ashr_i32 s35, s34, 31
	v_lshlrev_b32_e32 v170, 16, v158
	v_and_b32_e32 v171, 0xffff0000, v158
	v_lshlrev_b32_e32 v158, 16, v159
	v_and_b32_e32 v159, 0xffff0000, v159
	v_lshlrev_b32_e32 v172, 16, v160
	v_and_b32_e32 v173, 0xffff0000, v160
	v_lshlrev_b32_e32 v160, 16, v161
	v_and_b32_e32 v161, 0xffff0000, v161
	v_pk_fma_f32 v[128:129], v[164:165], v[158:159], v[128:129] op_sel_hi:[0,1,1]
	v_pk_fma_f32 v[170:171], v[164:165], v[170:171], v[126:127] op_sel_hi:[0,1,1]
	v_pk_fma_f32 v[178:179], v[164:165], v[160:161], v[124:125] op_sel_hi:[0,1,1]
	v_pk_fma_f32 v[172:173], v[164:165], v[172:173], v[122:123] op_sel_hi:[0,1,1]
	v_cvt_pk_bf16_f32 v124, v170, v171
	v_cvt_pk_bf16_f32 v125, v128, v129
	v_cvt_pk_bf16_f32 v126, v172, v173
	v_cvt_pk_bf16_f32 v127, v178, v179
	s_waitcnt vmcnt(22)
	v_mov_b32_e32 v158, v184
	v_mov_b32_e32 v159, v185
	v_mov_b32_e32 v160, v186
	v_mov_b32_e32 v161, v187
	v_mul_f32_e32 v168, v171, v171
	v_mul_f32_e32 v129, v129, v129
	v_mul_f32_e32 v169, v173, v173
	v_mul_f32_e32 v171, v179, v179
	v_fmac_f32_e32 v168, v170, v170
	v_fmac_f32_e32 v129, v128, v128
	v_fmac_f32_e32 v169, v172, v172
	v_fmac_f32_e32 v171, v178, v178
	v_add_f32_e32 v128, v168, v129
	v_add_f32_e32 v129, v169, v171
	v_xor_b32_e32 v165, 32, v157
	v_add_f32_e32 v170, v128, v129
	v_and_b32_e32 v123, 64, v157
	v_xor_b32_e32 v122, 16, v157
	v_add_u32_e32 v123, 64, v123
	v_cmp_lt_i32_e32 vcc, v122, v123
	global_store_dwordx4 v[166:167], v[124:127], off
	v_lshlrev_b32_e32 v128, 16, v158
	v_and_b32_e32 v129, 0xffff0000, v158
	v_lshlrev_b32_e32 v158, 16, v159
	v_and_b32_e32 v159, 0xffff0000, v159
	v_lshlrev_b32_e32 v168, 16, v160
	v_and_b32_e32 v169, 0xffff0000, v160
	v_lshlrev_b32_e32 v160, 16, v161
	v_and_b32_e32 v161, 0xffff0000, v161
	v_pk_fma_f32 v[120:121], v[164:165], v[158:159], v[120:121] op_sel_hi:[0,1,1]
	v_pk_fma_f32 v[118:119], v[164:165], v[128:129], v[118:119] op_sel_hi:[0,1,1]
	v_pk_fma_f32 v[128:129], v[164:165], v[160:161], v[116:117] op_sel_hi:[0,1,1]
	v_pk_fma_f32 v[158:159], v[164:165], v[168:169], v[114:115] op_sel_hi:[0,1,1]
	v_mul_f32_e32 v114, v119, v119
	v_mul_f32_e32 v115, v121, v121
	v_mul_f32_e32 v116, v159, v159
	v_mul_f32_e32 v117, v129, v129
	v_fmac_f32_e32 v114, v118, v118
	v_fmac_f32_e32 v115, v120, v120
	v_fmac_f32_e32 v116, v158, v158
	v_fmac_f32_e32 v117, v128, v128
	v_add_f32_e32 v114, v114, v115
	v_add_f32_e32 v115, v116, v117
	v_cndmask_b32_e32 v122, v157, v122, vcc
	v_add_f32_e32 v114, v114, v115
	v_lshlrev_b32_e32 v122, 2, v122
	v_add_f32_e32 v114, v170, v114
	ds_bpermute_b32 v115, v122, v114
	v_cmp_lt_i32_e32 vcc, v165, v123
	v_lshl_add_u64 v[124:125], s[6:7], 0, v[162:163]
	v_cvt_pk_bf16_f32 v118, v118, v119
	v_cvt_pk_bf16_f32 v119, v120, v121
	s_waitcnt lgkmcnt(0)
	v_add_f32_e32 v114, v114, v115
	v_cndmask_b32_e32 v116, v157, v165, vcc
	v_lshlrev_b32_e32 v116, 2, v116
	ds_bpermute_b32 v115, v116, v114
	v_cvt_pk_bf16_f32 v120, v158, v159
	v_cvt_pk_bf16_f32 v121, v128, v129
	global_store_dwordx4 v[124:125], v[118:121], off
	s_and_saveexec_b64 s[36:37], s[0:1]
	s_cbranch_execz .LBB0_1229
	v_lshlrev_b64 v[118:119], 6, v[148:149]
	v_lshl_add_u64 v[118:119], s[8:9], 0, v[118:119]
	v_lshl_add_u64 v[118:119], s[34:35], 2, v[118:119]
	s_lshl_b32 s12, s48, 2
	v_lshl_add_u64 v[118:119], v[118:119], 0, s[12:13]
	s_waitcnt lgkmcnt(0)
	v_add_f32_e32 v114, v114, v115
	global_store_dword v[118:119], v114, off
.LBB0_1229:
	s_or_b64 exec, exec, s[36:37]
	v_or_b32_e32 v114, 16, v148
	s_waitcnt lgkmcnt(0)
	v_ashrrev_i32_e32 v115, 31, v114
	v_lshlrev_b64 v[118:119], 10, v[114:115]
	v_lshl_add_u64 v[118:119], v[118:119], 0, v[146:147]
	v_lshlrev_b64 v[124:125], 1, v[118:119]
	v_lshl_add_u64 v[118:119], s[96:97], 0, v[124:125]
	s_waitcnt vmcnt(21)
	v_mov_b32_e32 v118, v188
	v_mov_b32_e32 v119, v189
	v_mov_b32_e32 v120, v190
	v_mov_b32_e32 v121, v191
	v_lshl_add_u64 v[126:127], v[114:115], 2, s[10:11]
	v_mov_b32_e32 v126, v245
	v_lshl_add_u64 v[128:129], s[6:7], 0, v[124:125]
	v_or_b32_e32 v124, 0x100, v124
	v_lshl_add_u64 v[158:159], s[96:97], 0, v[124:125]
	v_lshlrev_b32_e32 v160, 16, v118
	v_and_b32_e32 v161, 0xffff0000, v118
	v_lshlrev_b32_e32 v118, 16, v119
	v_and_b32_e32 v119, 0xffff0000, v119
	v_lshlrev_b32_e32 v162, 16, v120
	v_and_b32_e32 v163, 0xffff0000, v120
	v_lshlrev_b32_e32 v120, 16, v121
	v_and_b32_e32 v121, 0xffff0000, v121
	v_pk_fma_f32 v[118:119], v[126:127], v[118:119], v[112:113] op_sel_hi:[0,1,1]
	v_pk_fma_f32 v[160:161], v[126:127], v[160:161], v[110:111] op_sel_hi:[0,1,1]
	v_pk_fma_f32 v[120:121], v[126:127], v[120:121], v[108:109] op_sel_hi:[0,1,1]
	v_pk_fma_f32 v[162:163], v[126:127], v[162:163], v[106:107] op_sel_hi:[0,1,1]
	v_cvt_pk_bf16_f32 v106, v160, v161
	v_cvt_pk_bf16_f32 v107, v118, v119
	v_cvt_pk_bf16_f32 v108, v162, v163
	v_cvt_pk_bf16_f32 v109, v120, v121
	s_waitcnt vmcnt(21)
	v_mov_b32_e32 v110, v192
	v_mov_b32_e32 v111, v193
	v_mov_b32_e32 v112, v194
	v_mov_b32_e32 v113, v195
	v_mul_f32_e32 v117, v161, v161
	v_mul_f32_e32 v119, v119, v119
	v_mul_f32_e32 v123, v163, v163
	v_mul_f32_e32 v121, v121, v121
	v_fmac_f32_e32 v117, v160, v160
	v_fmac_f32_e32 v119, v118, v118
	v_fmac_f32_e32 v123, v162, v162
	v_fmac_f32_e32 v121, v120, v120
	v_add_f32_e32 v117, v117, v119
	v_add_f32_e32 v118, v123, v121
	v_add_f32_e32 v117, v117, v118
	global_store_dwordx4 v[128:129], v[106:109], off
	v_lshlrev_b32_e32 v118, 16, v110
	v_and_b32_e32 v119, 0xffff0000, v110
	v_lshlrev_b32_e32 v110, 16, v111
	v_and_b32_e32 v111, 0xffff0000, v111
	v_lshlrev_b32_e32 v120, 16, v112
	v_and_b32_e32 v121, 0xffff0000, v112
	v_lshlrev_b32_e32 v112, 16, v113
	v_and_b32_e32 v113, 0xffff0000, v113
	v_pk_fma_f32 v[104:105], v[126:127], v[110:111], v[104:105] op_sel_hi:[0,1,1]
	v_pk_fma_f32 v[102:103], v[126:127], v[118:119], v[102:103] op_sel_hi:[0,1,1]
	v_pk_fma_f32 v[110:111], v[126:127], v[112:113], v[100:101] op_sel_hi:[0,1,1]
	v_pk_fma_f32 v[112:113], v[126:127], v[120:121], v[98:99] op_sel_hi:[0,1,1]
	v_mul_f32_e32 v98, v103, v103
	v_mul_f32_e32 v99, v105, v105
	v_mul_f32_e32 v100, v113, v113
	v_mul_f32_e32 v101, v111, v111
	v_fmac_f32_e32 v98, v102, v102
	v_fmac_f32_e32 v99, v104, v104
	v_fmac_f32_e32 v100, v112, v112
	v_fmac_f32_e32 v101, v110, v110
	v_add_f32_e32 v98, v98, v99
	v_add_f32_e32 v99, v100, v101
	v_add_f32_e32 v98, v98, v99
	v_add_f32_e32 v98, v117, v98
	ds_bpermute_b32 v99, v122, v98
	v_cvt_pk_bf16_f32 v100, v102, v103
	v_cvt_pk_bf16_f32 v101, v104, v105
	v_lshl_add_u64 v[104:105], s[6:7], 0, v[124:125]
	v_cvt_pk_bf16_f32 v102, v112, v113
	s_waitcnt lgkmcnt(0)
	v_add_f32_e32 v98, v98, v99
	ds_bpermute_b32 v99, v116, v98
	v_cvt_pk_bf16_f32 v103, v110, v111
	global_store_dwordx4 v[104:105], v[100:103], off
	s_and_saveexec_b64 s[36:37], s[0:1]
	s_cbranch_execz .LBB0_1231
	v_lshlrev_b64 v[100:101], 6, v[114:115]
	v_lshl_add_u64 v[100:101], s[8:9], 0, v[100:101]
	v_lshl_add_u64 v[100:101], s[34:35], 2, v[100:101]
	s_lshl_b32 s12, s48, 2
	v_lshl_add_u64 v[100:101], v[100:101], 0, s[12:13]
	s_waitcnt lgkmcnt(0)
	v_add_f32_e32 v98, v98, v99
	global_store_dword v[100:101], v98, off
.LBB0_1231:
	s_or_b64 exec, exec, s[36:37]
	v_or_b32_e32 v98, 32, v148
	s_waitcnt lgkmcnt(0)
	v_ashrrev_i32_e32 v99, 31, v98
	v_lshlrev_b64 v[100:101], 10, v[98:99]
	v_lshl_add_u64 v[100:101], v[100:101], 0, v[146:147]
	v_lshlrev_b64 v[104:105], 1, v[100:101]
	v_lshl_add_u64 v[100:101], s[96:97], 0, v[104:105]
	s_waitcnt vmcnt(20)
	v_mov_b32_e32 v100, v196
	v_mov_b32_e32 v101, v197
	v_mov_b32_e32 v102, v198
	v_mov_b32_e32 v103, v199
	v_lshl_add_u64 v[106:107], v[98:99], 2, s[10:11]
	v_mov_b32_e32 v106, v246
	v_lshl_add_u64 v[108:109], s[6:7], 0, v[104:105]
	v_or_b32_e32 v104, 0x100, v104
	v_lshl_add_u64 v[110:111], s[96:97], 0, v[104:105]
	v_lshlrev_b32_e32 v112, 16, v100
	v_and_b32_e32 v113, 0xffff0000, v100
	v_lshlrev_b32_e32 v100, 16, v101
	v_and_b32_e32 v101, 0xffff0000, v101
	v_lshlrev_b32_e32 v114, 16, v102
	v_and_b32_e32 v115, 0xffff0000, v102
	v_lshlrev_b32_e32 v102, 16, v103
	v_and_b32_e32 v103, 0xffff0000, v103
	v_pk_fma_f32 v[100:101], v[106:107], v[100:101], v[96:97] op_sel_hi:[0,1,1]
	v_pk_fma_f32 v[112:113], v[106:107], v[112:113], v[94:95] op_sel_hi:[0,1,1]
	v_pk_fma_f32 v[102:103], v[106:107], v[102:103], v[92:93] op_sel_hi:[0,1,1]
	v_pk_fma_f32 v[114:115], v[106:107], v[114:115], v[90:91] op_sel_hi:[0,1,1]
	v_cvt_pk_bf16_f32 v90, v112, v113
	v_cvt_pk_bf16_f32 v91, v100, v101
	v_cvt_pk_bf16_f32 v92, v114, v115
	v_cvt_pk_bf16_f32 v93, v102, v103
	s_waitcnt vmcnt(20)
	v_mov_b32_e32 v94, v200
	v_mov_b32_e32 v95, v201
	v_mov_b32_e32 v96, v202
	v_mov_b32_e32 v97, v203
	v_mul_f32_e32 v107, v113, v113
	v_mul_f32_e32 v101, v101, v101
	v_mul_f32_e32 v110, v115, v115
	v_mul_f32_e32 v103, v103, v103
	v_fmac_f32_e32 v107, v112, v112
	v_fmac_f32_e32 v101, v100, v100
	v_fmac_f32_e32 v110, v114, v114
	v_fmac_f32_e32 v103, v102, v102
	v_add_f32_e32 v100, v107, v101
	v_add_f32_e32 v101, v110, v103
	v_add_f32_e32 v107, v100, v101
	global_store_dwordx4 v[108:109], v[90:93], off
	v_lshlrev_b32_e32 v100, 16, v94
	v_and_b32_e32 v101, 0xffff0000, v94
	v_lshlrev_b32_e32 v94, 16, v95
	v_and_b32_e32 v95, 0xffff0000, v95
	v_lshlrev_b32_e32 v102, 16, v96
	v_and_b32_e32 v103, 0xffff0000, v96
	v_lshlrev_b32_e32 v96, 16, v97
	v_and_b32_e32 v97, 0xffff0000, v97
	v_pk_fma_f32 v[88:89], v[106:107], v[94:95], v[88:89] op_sel_hi:[0,1,1]
	v_pk_fma_f32 v[86:87], v[106:107], v[100:101], v[86:87] op_sel_hi:[0,1,1]
	v_pk_fma_f32 v[94:95], v[106:107], v[96:97], v[84:85] op_sel_hi:[0,1,1]
	v_pk_fma_f32 v[96:97], v[106:107], v[102:103], v[82:83] op_sel_hi:[0,1,1]
	v_mul_f32_e32 v82, v87, v87
	v_mul_f32_e32 v83, v89, v89
	v_mul_f32_e32 v84, v97, v97
	v_mul_f32_e32 v85, v95, v95
	v_fmac_f32_e32 v82, v86, v86
	v_fmac_f32_e32 v83, v88, v88
	v_fmac_f32_e32 v84, v96, v96
	v_fmac_f32_e32 v85, v94, v94
	v_add_f32_e32 v82, v82, v83
	v_add_f32_e32 v83, v84, v85
	v_add_f32_e32 v82, v82, v83
	v_add_f32_e32 v82, v107, v82
	ds_bpermute_b32 v83, v122, v82
	v_cvt_pk_bf16_f32 v84, v86, v87
	v_cvt_pk_bf16_f32 v85, v88, v89
	v_lshl_add_u64 v[88:89], s[6:7], 0, v[104:105]
	v_cvt_pk_bf16_f32 v86, v96, v97
	s_waitcnt lgkmcnt(0)
	v_add_f32_e32 v82, v82, v83
	ds_bpermute_b32 v83, v116, v82
	v_cvt_pk_bf16_f32 v87, v94, v95
	global_store_dwordx4 v[88:89], v[84:87], off
	s_and_saveexec_b64 s[36:37], s[0:1]
	s_cbranch_execz .LBB0_1233
	v_lshlrev_b64 v[84:85], 6, v[98:99]
	v_lshl_add_u64 v[84:85], s[8:9], 0, v[84:85]
	v_lshl_add_u64 v[84:85], s[34:35], 2, v[84:85]
	s_lshl_b32 s12, s48, 2
	v_lshl_add_u64 v[84:85], v[84:85], 0, s[12:13]
	s_waitcnt lgkmcnt(0)
	v_add_f32_e32 v82, v82, v83
	global_store_dword v[84:85], v82, off
.LBB0_1233:
	s_or_b64 exec, exec, s[36:37]
	v_or_b32_e32 v82, 48, v148
	s_waitcnt lgkmcnt(0)
	v_ashrrev_i32_e32 v83, 31, v82
	v_lshlrev_b64 v[84:85], 10, v[82:83]
	v_lshl_add_u64 v[84:85], v[84:85], 0, v[146:147]
	v_lshlrev_b64 v[88:89], 1, v[84:85]
	v_lshl_add_u64 v[84:85], s[96:97], 0, v[88:89]
	s_waitcnt vmcnt(19)
	v_mov_b32_e32 v84, v204
	v_mov_b32_e32 v85, v205
	v_mov_b32_e32 v86, v206
	v_mov_b32_e32 v87, v207
	v_lshl_add_u64 v[90:91], v[82:83], 2, s[10:11]
	v_mov_b32_e32 v90, v247
	v_lshl_add_u64 v[92:93], s[6:7], 0, v[88:89]
	v_or_b32_e32 v88, 0x100, v88
	v_lshl_add_u64 v[94:95], s[96:97], 0, v[88:89]
	v_lshlrev_b32_e32 v96, 16, v84
	v_and_b32_e32 v97, 0xffff0000, v84
	v_lshlrev_b32_e32 v84, 16, v85
	v_and_b32_e32 v85, 0xffff0000, v85
	v_lshlrev_b32_e32 v98, 16, v86
	v_and_b32_e32 v99, 0xffff0000, v86
	v_lshlrev_b32_e32 v86, 16, v87
	v_and_b32_e32 v87, 0xffff0000, v87
	v_pk_fma_f32 v[84:85], v[90:91], v[84:85], v[80:81] op_sel_hi:[0,1,1]
	v_pk_fma_f32 v[96:97], v[90:91], v[96:97], v[78:79] op_sel_hi:[0,1,1]
	v_pk_fma_f32 v[86:87], v[90:91], v[86:87], v[76:77] op_sel_hi:[0,1,1]
	v_pk_fma_f32 v[98:99], v[90:91], v[98:99], v[74:75] op_sel_hi:[0,1,1]
	v_cvt_pk_bf16_f32 v74, v96, v97
	v_cvt_pk_bf16_f32 v75, v84, v85
	v_cvt_pk_bf16_f32 v76, v98, v99
	v_cvt_pk_bf16_f32 v77, v86, v87
	s_waitcnt vmcnt(19)
	v_mov_b32_e32 v78, v208
	v_mov_b32_e32 v79, v209
	v_mov_b32_e32 v80, v210
	v_mov_b32_e32 v81, v211
	v_mul_f32_e32 v91, v97, v97
	v_mul_f32_e32 v85, v85, v85
	v_mul_f32_e32 v94, v99, v99
	v_mul_f32_e32 v87, v87, v87
	v_fmac_f32_e32 v91, v96, v96
	v_fmac_f32_e32 v85, v84, v84
	v_fmac_f32_e32 v94, v98, v98
	v_fmac_f32_e32 v87, v86, v86
	v_add_f32_e32 v84, v91, v85
	v_add_f32_e32 v85, v94, v87
	v_add_f32_e32 v91, v84, v85
	global_store_dwordx4 v[92:93], v[74:77], off
	v_lshlrev_b32_e32 v84, 16, v78
	v_and_b32_e32 v85, 0xffff0000, v78
	v_lshlrev_b32_e32 v78, 16, v79
	v_and_b32_e32 v79, 0xffff0000, v79
	v_lshlrev_b32_e32 v86, 16, v80
	v_and_b32_e32 v87, 0xffff0000, v80
	v_lshlrev_b32_e32 v80, 16, v81
	v_and_b32_e32 v81, 0xffff0000, v81
	v_pk_fma_f32 v[72:73], v[90:91], v[78:79], v[72:73] op_sel_hi:[0,1,1]
	v_pk_fma_f32 v[70:71], v[90:91], v[84:85], v[70:71] op_sel_hi:[0,1,1]
	v_pk_fma_f32 v[78:79], v[90:91], v[80:81], v[68:69] op_sel_hi:[0,1,1]
	v_pk_fma_f32 v[80:81], v[90:91], v[86:87], v[66:67] op_sel_hi:[0,1,1]
	v_mul_f32_e32 v66, v71, v71
	v_mul_f32_e32 v67, v73, v73
	v_mul_f32_e32 v68, v81, v81
	v_mul_f32_e32 v69, v79, v79
	v_fmac_f32_e32 v66, v70, v70
	v_fmac_f32_e32 v67, v72, v72
	v_fmac_f32_e32 v68, v80, v80
	v_fmac_f32_e32 v69, v78, v78
	v_add_f32_e32 v66, v66, v67
	v_add_f32_e32 v67, v68, v69
	v_add_f32_e32 v66, v66, v67
	v_add_f32_e32 v66, v91, v66
	ds_bpermute_b32 v67, v122, v66
	v_cvt_pk_bf16_f32 v68, v70, v71
	v_cvt_pk_bf16_f32 v69, v72, v73
	v_lshl_add_u64 v[72:73], s[6:7], 0, v[88:89]
	v_cvt_pk_bf16_f32 v70, v80, v81
	s_waitcnt lgkmcnt(0)
	v_add_f32_e32 v66, v66, v67
	ds_bpermute_b32 v67, v116, v66
	v_cvt_pk_bf16_f32 v71, v78, v79
	global_store_dwordx4 v[72:73], v[68:71], off
	s_and_saveexec_b64 s[36:37], s[0:1]
	s_cbranch_execz .LBB0_1235
	v_lshlrev_b64 v[68:69], 6, v[82:83]
	v_lshl_add_u64 v[68:69], s[8:9], 0, v[68:69]
	v_lshl_add_u64 v[68:69], s[34:35], 2, v[68:69]
	s_lshl_b32 s12, s48, 2
	v_lshl_add_u64 v[68:69], v[68:69], 0, s[12:13]
	s_waitcnt lgkmcnt(0)
	v_add_f32_e32 v66, v66, v67
	global_store_dword v[68:69], v66, off
.LBB0_1235:
	s_or_b64 exec, exec, s[36:37]
	v_add_u32_e32 v66, 0x80, v148
	s_waitcnt lgkmcnt(0)
	v_ashrrev_i32_e32 v67, 31, v66
	v_lshlrev_b64 v[68:69], 10, v[66:67]
	v_lshl_add_u64 v[68:69], v[68:69], 0, v[146:147]
	v_lshlrev_b64 v[72:73], 1, v[68:69]
	v_lshl_add_u64 v[68:69], s[96:97], 0, v[72:73]
	s_waitcnt vmcnt(18)
	v_mov_b32_e32 v68, v212
	v_mov_b32_e32 v69, v213
	v_mov_b32_e32 v70, v214
	v_mov_b32_e32 v71, v215
	s_nop 0
	v_mov_b32_e32 v74, v248
	v_lshl_add_u64 v[76:77], s[6:7], 0, v[72:73]
	v_or_b32_e32 v72, 0x100, v72
	v_lshl_add_u64 v[78:79], s[96:97], 0, v[72:73]
	v_lshlrev_b32_e32 v80, 16, v68
	v_and_b32_e32 v81, 0xffff0000, v68
	v_lshlrev_b32_e32 v68, 16, v69
	v_and_b32_e32 v69, 0xffff0000, v69
	v_lshlrev_b32_e32 v82, 16, v70
	v_and_b32_e32 v83, 0xffff0000, v70
	v_lshlrev_b32_e32 v70, 16, v71
	v_and_b32_e32 v71, 0xffff0000, v71
	v_pk_fma_f32 v[68:69], v[74:75], v[68:69], v[64:65] op_sel_hi:[0,1,1]
	v_pk_fma_f32 v[80:81], v[74:75], v[80:81], v[62:63] op_sel_hi:[0,1,1]
	v_pk_fma_f32 v[70:71], v[74:75], v[70:71], v[60:61] op_sel_hi:[0,1,1]
	v_pk_fma_f32 v[82:83], v[74:75], v[82:83], v[58:59] op_sel_hi:[0,1,1]
	v_cvt_pk_bf16_f32 v58, v80, v81
	v_cvt_pk_bf16_f32 v59, v68, v69
	v_cvt_pk_bf16_f32 v60, v82, v83
	v_cvt_pk_bf16_f32 v61, v70, v71
	s_waitcnt vmcnt(18)
	v_mov_b32_e32 v62, v216
	v_mov_b32_e32 v63, v217
	v_mov_b32_e32 v64, v218
	v_mov_b32_e32 v65, v219
	v_mul_f32_e32 v75, v81, v81
	v_mul_f32_e32 v69, v69, v69
	v_mul_f32_e32 v78, v83, v83
	v_mul_f32_e32 v71, v71, v71
	v_fmac_f32_e32 v75, v80, v80
	v_fmac_f32_e32 v69, v68, v68
	v_fmac_f32_e32 v78, v82, v82
	v_fmac_f32_e32 v71, v70, v70
	v_add_f32_e32 v68, v75, v69
	v_add_f32_e32 v69, v78, v71
	v_add_f32_e32 v75, v68, v69
	global_store_dwordx4 v[76:77], v[58:61], off
	v_lshlrev_b32_e32 v68, 16, v62
	v_and_b32_e32 v69, 0xffff0000, v62
	v_lshlrev_b32_e32 v62, 16, v63
	v_and_b32_e32 v63, 0xffff0000, v63
	v_lshlrev_b32_e32 v70, 16, v64
	v_and_b32_e32 v71, 0xffff0000, v64
	v_lshlrev_b32_e32 v64, 16, v65
	v_and_b32_e32 v65, 0xffff0000, v65
	v_pk_fma_f32 v[56:57], v[74:75], v[62:63], v[56:57] op_sel_hi:[0,1,1]
	v_pk_fma_f32 v[54:55], v[74:75], v[68:69], v[54:55] op_sel_hi:[0,1,1]
	v_pk_fma_f32 v[62:63], v[74:75], v[64:65], v[52:53] op_sel_hi:[0,1,1]
	v_pk_fma_f32 v[64:65], v[74:75], v[70:71], v[50:51] op_sel_hi:[0,1,1]
	v_mul_f32_e32 v50, v55, v55
	v_mul_f32_e32 v51, v57, v57
	v_mul_f32_e32 v52, v65, v65
	v_mul_f32_e32 v53, v63, v63
	v_fmac_f32_e32 v50, v54, v54
	v_fmac_f32_e32 v51, v56, v56
	v_fmac_f32_e32 v52, v64, v64
	v_fmac_f32_e32 v53, v62, v62
	v_add_f32_e32 v50, v50, v51
	v_add_f32_e32 v51, v52, v53
	v_add_f32_e32 v50, v50, v51
	v_add_f32_e32 v50, v75, v50
	ds_bpermute_b32 v51, v122, v50
	v_cvt_pk_bf16_f32 v52, v54, v55
	v_cvt_pk_bf16_f32 v53, v56, v57
	v_lshl_add_u64 v[56:57], s[6:7], 0, v[72:73]
	v_cvt_pk_bf16_f32 v54, v64, v65
	s_waitcnt lgkmcnt(0)
	v_add_f32_e32 v50, v50, v51
	ds_bpermute_b32 v51, v116, v50
	v_cvt_pk_bf16_f32 v55, v62, v63
	global_store_dwordx4 v[56:57], v[52:55], off
	s_and_saveexec_b64 s[36:37], s[0:1]
	s_cbranch_execz .LBB0_1237
	v_lshlrev_b64 v[52:53], 6, v[66:67]
	v_lshl_add_u64 v[52:53], s[8:9], 0, v[52:53]
	v_lshl_add_u64 v[52:53], s[34:35], 2, v[52:53]
	s_lshl_b32 s12, s48, 2
	v_lshl_add_u64 v[52:53], v[52:53], 0, s[12:13]
	s_waitcnt lgkmcnt(0)
	v_add_f32_e32 v50, v50, v51
	global_store_dword v[52:53], v50, off
.LBB0_1237:
	s_or_b64 exec, exec, s[36:37]
	v_add_u32_e32 v50, 0x90, v148
	s_waitcnt lgkmcnt(0)
	v_ashrrev_i32_e32 v51, 31, v50
	v_lshlrev_b64 v[52:53], 10, v[50:51]
	v_lshl_add_u64 v[52:53], v[52:53], 0, v[146:147]
	v_lshlrev_b64 v[56:57], 1, v[52:53]
	v_lshl_add_u64 v[52:53], s[96:97], 0, v[56:57]
	s_waitcnt vmcnt(17)
	v_mov_b32_e32 v52, v220
	v_mov_b32_e32 v53, v221
	v_mov_b32_e32 v54, v222
	v_mov_b32_e32 v55, v223
	s_nop 0
	v_mov_b32_e32 v58, v249
	v_lshl_add_u64 v[60:61], s[6:7], 0, v[56:57]
	v_or_b32_e32 v56, 0x100, v56
	v_lshl_add_u64 v[62:63], s[96:97], 0, v[56:57]
	v_lshlrev_b32_e32 v64, 16, v52
	v_and_b32_e32 v65, 0xffff0000, v52
	v_lshlrev_b32_e32 v52, 16, v53
	v_and_b32_e32 v53, 0xffff0000, v53
	v_lshlrev_b32_e32 v66, 16, v54
	v_and_b32_e32 v67, 0xffff0000, v54
	v_lshlrev_b32_e32 v54, 16, v55
	v_and_b32_e32 v55, 0xffff0000, v55
	v_pk_fma_f32 v[52:53], v[58:59], v[52:53], v[48:49] op_sel_hi:[0,1,1]
	v_pk_fma_f32 v[64:65], v[58:59], v[64:65], v[46:47] op_sel_hi:[0,1,1]
	v_pk_fma_f32 v[54:55], v[58:59], v[54:55], v[44:45] op_sel_hi:[0,1,1]
	v_pk_fma_f32 v[66:67], v[58:59], v[66:67], v[42:43] op_sel_hi:[0,1,1]
	v_cvt_pk_bf16_f32 v42, v64, v65
	v_cvt_pk_bf16_f32 v43, v52, v53
	v_cvt_pk_bf16_f32 v44, v66, v67
	v_cvt_pk_bf16_f32 v45, v54, v55
	s_waitcnt vmcnt(17)
	v_mov_b32_e32 v46, v224
	v_mov_b32_e32 v47, v225
	v_mov_b32_e32 v48, v226
	v_mov_b32_e32 v49, v227
	v_mul_f32_e32 v59, v65, v65
	v_mul_f32_e32 v53, v53, v53
	v_mul_f32_e32 v62, v67, v67
	v_mul_f32_e32 v55, v55, v55
	v_fmac_f32_e32 v59, v64, v64
	v_fmac_f32_e32 v53, v52, v52
	v_fmac_f32_e32 v62, v66, v66
	v_fmac_f32_e32 v55, v54, v54
	v_add_f32_e32 v52, v59, v53
	v_add_f32_e32 v53, v62, v55
	v_add_f32_e32 v59, v52, v53
	global_store_dwordx4 v[60:61], v[42:45], off
	v_lshlrev_b32_e32 v52, 16, v46
	v_and_b32_e32 v53, 0xffff0000, v46
	v_lshlrev_b32_e32 v46, 16, v47
	v_and_b32_e32 v47, 0xffff0000, v47
	v_lshlrev_b32_e32 v54, 16, v48
	v_and_b32_e32 v55, 0xffff0000, v48
	v_lshlrev_b32_e32 v48, 16, v49
	v_and_b32_e32 v49, 0xffff0000, v49
	v_pk_fma_f32 v[40:41], v[58:59], v[46:47], v[40:41] op_sel_hi:[0,1,1]
	v_pk_fma_f32 v[38:39], v[58:59], v[52:53], v[38:39] op_sel_hi:[0,1,1]
	v_pk_fma_f32 v[46:47], v[58:59], v[48:49], v[36:37] op_sel_hi:[0,1,1]
	v_pk_fma_f32 v[48:49], v[58:59], v[54:55], v[34:35] op_sel_hi:[0,1,1]
	v_mul_f32_e32 v34, v39, v39
	v_mul_f32_e32 v35, v41, v41
	v_mul_f32_e32 v36, v49, v49
	v_mul_f32_e32 v37, v47, v47
	v_fmac_f32_e32 v34, v38, v38
	v_fmac_f32_e32 v35, v40, v40
	v_fmac_f32_e32 v36, v48, v48
	v_fmac_f32_e32 v37, v46, v46
	v_add_f32_e32 v34, v34, v35
	v_add_f32_e32 v35, v36, v37
	v_add_f32_e32 v34, v34, v35
	v_add_f32_e32 v34, v59, v34
	ds_bpermute_b32 v35, v122, v34
	v_cvt_pk_bf16_f32 v36, v38, v39
	v_cvt_pk_bf16_f32 v37, v40, v41
	v_lshl_add_u64 v[40:41], s[6:7], 0, v[56:57]
	v_cvt_pk_bf16_f32 v38, v48, v49
	s_waitcnt lgkmcnt(0)
	v_add_f32_e32 v34, v34, v35
	ds_bpermute_b32 v35, v116, v34
	v_cvt_pk_bf16_f32 v39, v46, v47
	global_store_dwordx4 v[40:41], v[36:39], off
	s_and_saveexec_b64 s[36:37], s[0:1]
	s_cbranch_execz .LBB0_1239
	v_lshlrev_b64 v[36:37], 6, v[50:51]
	v_lshl_add_u64 v[36:37], s[8:9], 0, v[36:37]
	v_lshl_add_u64 v[36:37], s[34:35], 2, v[36:37]
	s_lshl_b32 s12, s48, 2
	v_lshl_add_u64 v[36:37], v[36:37], 0, s[12:13]
	s_waitcnt lgkmcnt(0)
	v_add_f32_e32 v34, v34, v35
	global_store_dword v[36:37], v34, off
.LBB0_1239:
	s_or_b64 exec, exec, s[36:37]
	v_add_u32_e32 v34, 0xa0, v148
	s_waitcnt lgkmcnt(0)
	v_ashrrev_i32_e32 v35, 31, v34
	v_lshlrev_b64 v[36:37], 10, v[34:35]
	v_lshl_add_u64 v[36:37], v[36:37], 0, v[146:147]
	v_lshlrev_b64 v[40:41], 1, v[36:37]
	v_lshl_add_u64 v[36:37], s[96:97], 0, v[40:41]
	s_waitcnt vmcnt(16)
	v_mov_b32_e32 v36, v228
	v_mov_b32_e32 v37, v229
	v_mov_b32_e32 v38, v230
	v_mov_b32_e32 v39, v231
	s_nop 0
	v_mov_b32_e32 v42, v250
	v_lshl_add_u64 v[44:45], s[6:7], 0, v[40:41]
	v_or_b32_e32 v40, 0x100, v40
	v_lshl_add_u64 v[46:47], s[96:97], 0, v[40:41]
	v_lshlrev_b32_e32 v48, 16, v36
	v_and_b32_e32 v49, 0xffff0000, v36
	v_lshlrev_b32_e32 v36, 16, v37
	v_and_b32_e32 v37, 0xffff0000, v37
	v_lshlrev_b32_e32 v50, 16, v38
	v_and_b32_e32 v51, 0xffff0000, v38
	v_lshlrev_b32_e32 v38, 16, v39
	v_and_b32_e32 v39, 0xffff0000, v39
	v_pk_fma_f32 v[36:37], v[42:43], v[36:37], v[32:33] op_sel_hi:[0,1,1]
	v_pk_fma_f32 v[48:49], v[42:43], v[48:49], v[30:31] op_sel_hi:[0,1,1]
	v_pk_fma_f32 v[38:39], v[42:43], v[38:39], v[28:29] op_sel_hi:[0,1,1]
	v_pk_fma_f32 v[50:51], v[42:43], v[50:51], v[26:27] op_sel_hi:[0,1,1]
	v_cvt_pk_bf16_f32 v26, v48, v49
	v_cvt_pk_bf16_f32 v27, v36, v37
	v_cvt_pk_bf16_f32 v28, v50, v51
	v_cvt_pk_bf16_f32 v29, v38, v39
	s_waitcnt vmcnt(16)
	v_mov_b32_e32 v30, v232
	v_mov_b32_e32 v31, v233
	v_mov_b32_e32 v32, v234
	v_mov_b32_e32 v33, v235
	v_mul_f32_e32 v43, v49, v49
	v_mul_f32_e32 v37, v37, v37
	v_mul_f32_e32 v46, v51, v51
	v_mul_f32_e32 v39, v39, v39
	v_fmac_f32_e32 v43, v48, v48
	v_fmac_f32_e32 v37, v36, v36
	v_fmac_f32_e32 v46, v50, v50
	v_fmac_f32_e32 v39, v38, v38
	v_add_f32_e32 v36, v43, v37
	v_add_f32_e32 v37, v46, v39
	v_add_f32_e32 v43, v36, v37
	global_store_dwordx4 v[44:45], v[26:29], off
	v_lshlrev_b32_e32 v36, 16, v30
	v_and_b32_e32 v37, 0xffff0000, v30
	v_lshlrev_b32_e32 v30, 16, v31
	v_and_b32_e32 v31, 0xffff0000, v31
	v_lshlrev_b32_e32 v38, 16, v32
	v_and_b32_e32 v39, 0xffff0000, v32
	v_lshlrev_b32_e32 v32, 16, v33
	v_and_b32_e32 v33, 0xffff0000, v33
	v_pk_fma_f32 v[24:25], v[42:43], v[30:31], v[24:25] op_sel_hi:[0,1,1]
	v_pk_fma_f32 v[22:23], v[42:43], v[36:37], v[22:23] op_sel_hi:[0,1,1]
	v_pk_fma_f32 v[30:31], v[42:43], v[32:33], v[20:21] op_sel_hi:[0,1,1]
	v_pk_fma_f32 v[32:33], v[42:43], v[38:39], v[18:19] op_sel_hi:[0,1,1]
	v_mul_f32_e32 v18, v23, v23
	v_mul_f32_e32 v19, v25, v25
	v_mul_f32_e32 v20, v33, v33
	v_mul_f32_e32 v21, v31, v31
	v_fmac_f32_e32 v18, v22, v22
	v_fmac_f32_e32 v19, v24, v24
	v_fmac_f32_e32 v20, v32, v32
	v_fmac_f32_e32 v21, v30, v30
	v_add_f32_e32 v18, v18, v19
	v_add_f32_e32 v19, v20, v21
	v_add_f32_e32 v18, v18, v19
	v_add_f32_e32 v18, v43, v18
	ds_bpermute_b32 v19, v122, v18
	v_cvt_pk_bf16_f32 v20, v22, v23
	v_cvt_pk_bf16_f32 v21, v24, v25
	v_lshl_add_u64 v[24:25], s[6:7], 0, v[40:41]
	v_cvt_pk_bf16_f32 v22, v32, v33
	s_waitcnt lgkmcnt(0)
	v_add_f32_e32 v18, v18, v19
	ds_bpermute_b32 v19, v116, v18
	v_cvt_pk_bf16_f32 v23, v30, v31
	global_store_dwordx4 v[24:25], v[20:23], off
	s_and_saveexec_b64 s[36:37], s[0:1]
	s_cbranch_execz .LBB0_1241
	v_lshlrev_b64 v[20:21], 6, v[34:35]
	v_lshl_add_u64 v[20:21], s[8:9], 0, v[20:21]
	v_lshl_add_u64 v[20:21], s[34:35], 2, v[20:21]
	s_lshl_b32 s12, s48, 2
	v_lshl_add_u64 v[20:21], v[20:21], 0, s[12:13]
	s_waitcnt lgkmcnt(0)
	v_add_f32_e32 v18, v18, v19
	global_store_dword v[20:21], v18, off
.LBB0_1241:
	s_or_b64 exec, exec, s[36:37]
	v_add_u32_e32 v18, 0xb0, v148
	s_waitcnt lgkmcnt(0)
	v_ashrrev_i32_e32 v19, 31, v18
	v_lshlrev_b64 v[20:21], 10, v[18:19]
	v_lshl_add_u64 v[20:21], v[20:21], 0, v[146:147]
	v_lshlrev_b64 v[24:25], 1, v[20:21]
	v_lshl_add_u64 v[20:21], s[96:97], 0, v[24:25]
	s_waitcnt vmcnt(15)
	v_mov_b32_e32 v20, v236
	v_mov_b32_e32 v21, v237
	v_mov_b32_e32 v22, v238
	v_mov_b32_e32 v23, v239
	s_nop 0
	v_mov_b32_e32 v26, v251
	v_lshl_add_u64 v[28:29], s[6:7], 0, v[24:25]
	v_or_b32_e32 v24, 0x100, v24
	v_lshl_add_u64 v[30:31], s[96:97], 0, v[24:25]
	v_lshlrev_b32_e32 v32, 16, v20
	v_and_b32_e32 v33, 0xffff0000, v20
	v_lshlrev_b32_e32 v20, 16, v21
	v_and_b32_e32 v21, 0xffff0000, v21
	v_lshlrev_b32_e32 v34, 16, v22
	v_and_b32_e32 v35, 0xffff0000, v22
	v_lshlrev_b32_e32 v22, 16, v23
	v_and_b32_e32 v23, 0xffff0000, v23
	v_pk_fma_f32 v[20:21], v[26:27], v[20:21], v[16:17] op_sel_hi:[0,1,1]
	v_pk_fma_f32 v[32:33], v[26:27], v[32:33], v[14:15] op_sel_hi:[0,1,1]
	v_pk_fma_f32 v[22:23], v[26:27], v[22:23], v[12:13] op_sel_hi:[0,1,1]
	v_pk_fma_f32 v[34:35], v[26:27], v[34:35], v[10:11] op_sel_hi:[0,1,1]
	v_cvt_pk_bf16_f32 v10, v32, v33
	v_cvt_pk_bf16_f32 v11, v20, v21
	v_cvt_pk_bf16_f32 v12, v34, v35
	v_cvt_pk_bf16_f32 v13, v22, v23
	s_waitcnt vmcnt(15)
	v_mov_b32_e32 v14, v240
	v_mov_b32_e32 v15, v241
	v_mov_b32_e32 v16, v242
	v_mov_b32_e32 v17, v243
	v_mul_f32_e32 v27, v33, v33
	v_mul_f32_e32 v21, v21, v21
	v_mul_f32_e32 v30, v35, v35
	v_mul_f32_e32 v23, v23, v23
	v_fmac_f32_e32 v27, v32, v32
	v_fmac_f32_e32 v21, v20, v20
	v_fmac_f32_e32 v30, v34, v34
	v_fmac_f32_e32 v23, v22, v22
	v_add_f32_e32 v20, v27, v21
	v_add_f32_e32 v21, v30, v23
	v_add_f32_e32 v27, v20, v21
	global_store_dwordx4 v[28:29], v[10:13], off
	v_lshlrev_b32_e32 v20, 16, v14
	v_and_b32_e32 v21, 0xffff0000, v14
	v_lshlrev_b32_e32 v14, 16, v15
	v_and_b32_e32 v15, 0xffff0000, v15
	v_lshlrev_b32_e32 v22, 16, v16
	v_and_b32_e32 v23, 0xffff0000, v16
	v_lshlrev_b32_e32 v16, 16, v17
	v_and_b32_e32 v17, 0xffff0000, v17
	v_pk_fma_f32 v[8:9], v[26:27], v[14:15], v[8:9] op_sel_hi:[0,1,1]
	v_pk_fma_f32 v[6:7], v[26:27], v[20:21], v[6:7] op_sel_hi:[0,1,1]
	v_pk_fma_f32 v[14:15], v[26:27], v[16:17], v[4:5] op_sel_hi:[0,1,1]
	v_pk_fma_f32 v[16:17], v[26:27], v[22:23], v[2:3] op_sel_hi:[0,1,1]
	v_mul_f32_e32 v2, v7, v7
	v_mul_f32_e32 v3, v9, v9
	v_mul_f32_e32 v4, v17, v17
	v_mul_f32_e32 v5, v15, v15
	v_fmac_f32_e32 v2, v6, v6
	v_fmac_f32_e32 v3, v8, v8
	v_fmac_f32_e32 v4, v16, v16
	v_fmac_f32_e32 v5, v14, v14
	v_add_f32_e32 v2, v2, v3
	v_add_f32_e32 v3, v4, v5
	v_add_f32_e32 v2, v2, v3
	v_add_f32_e32 v2, v27, v2
	ds_bpermute_b32 v3, v122, v2
	v_cvt_pk_bf16_f32 v4, v6, v7
	v_cvt_pk_bf16_f32 v5, v8, v9
	v_lshl_add_u64 v[8:9], s[6:7], 0, v[24:25]
	v_cvt_pk_bf16_f32 v6, v16, v17
	s_waitcnt lgkmcnt(0)
	v_add_f32_e32 v2, v2, v3
	ds_bpermute_b32 v3, v116, v2
	v_cvt_pk_bf16_f32 v7, v14, v15
	global_store_dwordx4 v[8:9], v[4:7], off
	s_and_saveexec_b64 s[36:37], s[0:1]
	s_cbranch_execz .LBB0_1243
	v_lshlrev_b64 v[4:5], 6, v[18:19]
	v_lshl_add_u64 v[4:5], s[8:9], 0, v[4:5]
	v_lshl_add_u64 v[4:5], s[34:35], 2, v[4:5]
	s_lshl_b32 s12, s48, 2
	v_lshl_add_u64 v[4:5], v[4:5], 0, s[12:13]
	s_waitcnt lgkmcnt(0)
	v_add_f32_e32 v2, v2, v3
	global_store_dword v[4:5], v2, off
